# cache policy: nt on ROW2's read-once row loads (YK expert rows and residual)
# speedup vs baseline: 1.0197x; 1.0027x over previous
; __device__ __forceinline__ void phase_row2(const Frame& F, int l) {
;     ...
;         f32x4 g1[4], lg[4], lb[4], sc1[4], sh[4];
;         load_row8(modp + 5 * 1024, lane, g1); load_row8(F.in[12] + (l * 2 + 1) * D, lane, lg); load_row8(F.in[13] + (l * 2 + 1) * D, lane, lb);
; #pragma unroll
;         for (int j = 0; j < 4; ++j) g1[j] = g1[j] + 1.f;
;         if (l + 1 < DEPTH) { const float* modn = MOD + ((size_t)(l + 1) * 8 + b) * 6144; load_row8(modn, lane, sh); load_row8(modn + 1024, lane, sc1);
; #pragma unroll
;             for (int j = 0; j < 4; ++j) sc1[j] = sc1[j] + 1.f; }
;         else {
; #pragma unroll
;             for (int j = 0; j < 4; ++j) { sh[j] = (f32x4){0.f, 0.f, 0.f, 0.f}; sc1[j] = sh[j]; } }
;         u32x4 cxb[2], nxb[2], cy[4][2], ny[4][2];
;         { const bf16* yk = (const bf16*)(F.ws + WS_YK) + (size_t)row0 * 4 * D + 8 * lane;
; #pragma unroll
;           for (int j2 = 0; j2 < 2; ++j2) { cxb[j2] = *(const u32x4*)(XB + (size_t)row0 * D + 512 * j2 + 8 * lane);
; #pragma unroll
;               for (int k = 0; k < 4; ++k) cy[k][j2] = *(const u32x4*)(yk + k * D + 512 * j2); } }
.LBB0_2425:
	s_ashr_i32 s37, s36, 31
	s_lshl_b64 s[0:1], s[36:37], 13
	v_lshl_add_u64 v[50:51], v[112:113], 0, s[0:1]
	s_lshl_b64 s[0:1], s[36:37], 11
	v_lshl_add_u64 v[52:53], v[108:109], 0, s[0:1]
	v_add_co_u32_e32 v136, vcc, 0x1000, v50
	s_waitcnt vmcnt(11)
	v_pk_add_f32 v[148:149], v[100:101], 1.0 op_sel_hi:[1,0]
	v_addc_co_u32_e32 v137, vcc, 0, v51, vcc
	global_load_dwordx4 v[86:89], v[52:53], off nt
	global_load_dwordx4 v[66:69], v[52:53], off offset:1024 nt
	global_load_dwordx4 v[82:85], v[50:51], off nt
	global_load_dwordx4 v[62:65], v[50:51], off offset:1024 nt
	global_load_dwordx4 v[78:81], v[50:51], off offset:2048 nt
	global_load_dwordx4 v[58:61], v[50:51], off offset:3072 nt
	global_load_dwordx4 v[74:77], v[136:137], off nt
	global_load_dwordx4 v[54:57], v[136:137], off offset:1024 nt
	global_load_dwordx4 v[70:73], v[136:137], off offset:2048 nt
	s_nop 0
	global_load_dwordx4 v[50:53], v[136:137], off offset:3072 nt
	v_pk_add_f32 v[150:151], v[98:99], 1.0 op_sel_hi:[1,0]
	s_waitcnt vmcnt(19)
	v_pk_add_f32 v[144:145], v[104:105], 1.0 op_sel_hi:[1,0]
	v_pk_add_f32 v[146:147], v[102:103], 1.0 op_sel_hi:[1,0]
	s_waitcnt vmcnt(18)
	v_pk_add_f32 v[140:141], v[96:97], 1.0 op_sel_hi:[1,0]
	v_pk_add_f32 v[142:143], v[94:95], 1.0 op_sel_hi:[1,0]
	v_pk_add_f32 v[136:137], v[92:93], 1.0 op_sel_hi:[1,0]
	v_pk_add_f32 v[138:139], v[90:91], 1.0 op_sel_hi:[1,0]
	s_mov_b32 s10, 0
	s_branch .LBB0_2427

; __device__ __forceinline__ f32x4 bf4lo(u32x4 q) { return (f32x4){__uint_as_float(q.x << 16), __uint_as_float(q.x & 0xffff0000u), __uint_as_float(q.y << 16), __uint_as_float(q.y & 0xffff0000u)}; }
; __device__ __forceinline__ f32x4 bf4hi(u32x4 q) { return (f32x4){__uint_as_float(q.z << 16), __uint_as_float(q.z & 0xffff0000u), __uint_as_float(q.w << 16), __uint_as_float(q.w & 0xffff0000u)}; }
; __device__ __forceinline__ void deepnorm_r(f32x4 (&x)[4], const f32x4 (&y)[4], const f32x4 (&g1)[4], const f32x4 (&lg)[4], const f32x4 (&lb)[4]) {
; #pragma unroll
;     for (int j = 0; j < 4; ++j) x[j] = ALPHA * x[j] + g1[j] * y[j];
;     float mean, rstd; ln_stats(x, mean, rstd);
; __device__ __forceinline__ void phase_row2(const Frame& F, int l) {
;     ...
;             f32x4 x[4], y[4];
; #pragma unroll
;             for (int j2 = 0; j2 < 2; ++j2) { x[2 * j2] = bf4lo(cxb[j2]); x[2 * j2 + 1] = bf4hi(cxb[j2]);
;                 y[2 * j2] = (bf4lo(cy[0][j2]) + bf4lo(cy[1][j2])) + (bf4lo(cy[2][j2]) + bf4lo(cy[3][j2]));
;                 y[2 * j2 + 1] = (bf4hi(cy[0][j2]) + bf4hi(cy[1][j2])) + (bf4hi(cy[2][j2]) + bf4hi(cy[3][j2])); }
;             deepnorm_r(x, y, g1, lg, lb);
.LBB0_2427:
	s_waitcnt vmcnt(7)
	v_lshlrev_b32_e32 v94, 16, v82
	v_and_b32_e32 v95, 0xffff0000, v82
	v_lshlrev_b32_e32 v82, 16, v83
	v_and_b32_e32 v83, 0xffff0000, v83
	s_waitcnt vmcnt(5)
	v_lshlrev_b32_e32 v96, 16, v78
	v_and_b32_e32 v97, 0xffff0000, v78
	v_lshlrev_b32_e32 v78, 16, v79
	v_and_b32_e32 v79, 0xffff0000, v79
	v_pk_add_f32 v[94:95], v[96:97], v[94:95]
	v_pk_add_f32 v[78:79], v[78:79], v[82:83]
	s_waitcnt vmcnt(3)
	v_lshlrev_b32_e32 v82, 16, v74
	v_and_b32_e32 v83, 0xffff0000, v74
	v_lshlrev_b32_e32 v74, 16, v75
	v_and_b32_e32 v75, 0xffff0000, v75
	s_waitcnt vmcnt(1)
	v_lshlrev_b32_e32 v96, 16, v70
	v_and_b32_e32 v97, 0xffff0000, v70
	v_lshlrev_b32_e32 v70, 16, v71
	v_and_b32_e32 v71, 0xffff0000, v71
	v_pk_add_f32 v[82:83], v[96:97], v[82:83]
	v_pk_add_f32 v[70:71], v[70:71], v[74:75]
	v_pk_add_f32 v[74:75], v[82:83], v[94:95]
	v_pk_add_f32 v[70:71], v[70:71], v[78:79]
	v_lshlrev_b32_e32 v78, 16, v84
	v_and_b32_e32 v79, 0xffff0000, v84
	v_lshlrev_b32_e32 v82, 16, v85
	v_and_b32_e32 v83, 0xffff0000, v85
	v_lshlrev_b32_e32 v84, 16, v80
	v_and_b32_e32 v85, 0xffff0000, v80
	v_lshlrev_b32_e32 v80, 16, v81
	v_and_b32_e32 v81, 0xffff0000, v81
	v_pk_add_f32 v[78:79], v[84:85], v[78:79]
	v_pk_add_f32 v[80:81], v[80:81], v[82:83]
	v_lshlrev_b32_e32 v82, 16, v76
	v_and_b32_e32 v83, 0xffff0000, v76
	v_lshlrev_b32_e32 v84, 16, v72
	v_and_b32_e32 v85, 0xffff0000, v72
	v_lshlrev_b32_e32 v76, 16, v77
	v_and_b32_e32 v77, 0xffff0000, v77
	v_lshlrev_b32_e32 v72, 16, v73
	v_and_b32_e32 v73, 0xffff0000, v73
	v_pk_add_f32 v[82:83], v[84:85], v[82:83]
	v_pk_add_f32 v[72:73], v[72:73], v[76:77]
	v_pk_add_f32 v[76:77], v[82:83], v[78:79]
	v_lshlrev_b32_e32 v82, 16, v62
	v_and_b32_e32 v83, 0xffff0000, v62
	v_lshlrev_b32_e32 v62, 16, v63
	v_and_b32_e32 v63, 0xffff0000, v63
	v_lshlrev_b32_e32 v84, 16, v58
	v_and_b32_e32 v85, 0xffff0000, v58
	v_lshlrev_b32_e32 v58, 16, v59
	v_and_b32_e32 v59, 0xffff0000, v59
	v_pk_add_f32 v[82:83], v[84:85], v[82:83]
	v_pk_add_f32 v[58:59], v[58:59], v[62:63]
	v_lshlrev_b32_e32 v62, 16, v54
	v_and_b32_e32 v63, 0xffff0000, v54
	v_lshlrev_b32_e32 v54, 16, v55
	v_and_b32_e32 v55, 0xffff0000, v55
	s_waitcnt vmcnt(0)
	v_lshlrev_b32_e32 v84, 16, v50
	v_and_b32_e32 v85, 0xffff0000, v50
	v_lshlrev_b32_e32 v50, 16, v51
	v_and_b32_e32 v51, 0xffff0000, v51
	v_pk_add_f32 v[62:63], v[84:85], v[62:63]
	v_pk_add_f32 v[50:51], v[50:51], v[54:55]
	v_pk_add_f32 v[54:55], v[62:63], v[82:83]
	v_pk_add_f32 v[50:51], v[50:51], v[58:59]
	v_lshlrev_b32_e32 v58, 16, v64
	v_and_b32_e32 v59, 0xffff0000, v64
	v_lshlrev_b32_e32 v62, 16, v65
	v_and_b32_e32 v63, 0xffff0000, v65
	v_lshlrev_b32_e32 v64, 16, v60
	v_and_b32_e32 v65, 0xffff0000, v60
	v_lshlrev_b32_e32 v60, 16, v61
	v_and_b32_e32 v61, 0xffff0000, v61
	v_pk_add_f32 v[58:59], v[64:65], v[58:59]
	v_pk_add_f32 v[60:61], v[60:61], v[62:63]
	v_lshlrev_b32_e32 v62, 16, v56
	v_and_b32_e32 v63, 0xffff0000, v56
	v_lshlrev_b32_e32 v56, 16, v57
	v_and_b32_e32 v57, 0xffff0000, v57
	v_lshlrev_b32_e32 v64, 16, v52
	v_and_b32_e32 v65, 0xffff0000, v52
	v_lshlrev_b32_e32 v52, 16, v53
	v_and_b32_e32 v53, 0xffff0000, v53
	v_pk_add_f32 v[62:63], v[64:65], v[62:63]
	v_pk_add_f32 v[52:53], v[52:53], v[56:57]
	v_lshlrev_b32_e32 v90, 16, v86
	v_and_b32_e32 v91, 0xffff0000, v86
	v_lshlrev_b32_e32 v86, 16, v87
	v_and_b32_e32 v87, 0xffff0000, v87
	v_pk_add_f32 v[72:73], v[72:73], v[80:81]
	v_lshlrev_b32_e32 v78, 16, v66
	v_and_b32_e32 v79, 0xffff0000, v66
	v_lshlrev_b32_e32 v66, 16, v67
	v_and_b32_e32 v67, 0xffff0000, v67
	v_pk_add_f32 v[52:53], v[52:53], v[60:61]
	v_pk_add_f32 v[56:57], v[62:63], v[58:59]
	v_pk_mul_f32 v[58:59], v[150:151], v[74:75]
	v_pk_mul_f32 v[60:61], v[148:149], v[70:71]
	v_pk_mul_f32 v[50:51], v[140:141], v[50:51]
	v_lshlrev_b32_e32 v92, 16, v88
	v_and_b32_e32 v93, 0xffff0000, v88
	v_lshlrev_b32_e32 v88, 16, v89
	v_and_b32_e32 v89, 0xffff0000, v89
	v_lshlrev_b32_e32 v80, 16, v68
	v_and_b32_e32 v81, 0xffff0000, v68
	v_lshlrev_b32_e32 v68, 16, v69
	v_and_b32_e32 v69, 0xffff0000, v69
	v_pk_fma_f32 v[94:95], v[86:87], s[16:17], v[60:61] op_sel_hi:[1,0,1]
	v_pk_fma_f32 v[90:91], v[90:91], s[16:17], v[58:59] op_sel_hi:[1,0,1]
	v_pk_mul_f32 v[58:59], v[146:147], v[76:77]
	v_pk_mul_f32 v[60:61], v[144:145], v[72:73]
	v_pk_fma_f32 v[100:101], v[66:67], s[16:17], v[50:51] op_sel_hi:[1,0,1]
	v_pk_mul_f32 v[50:51], v[138:139], v[56:57]
	v_pk_mul_f32 v[52:53], v[136:137], v[52:53]
	v_pk_fma_f32 v[96:97], v[88:89], s[16:17], v[60:61] op_sel_hi:[1,0,1]
	v_pk_fma_f32 v[98:99], v[92:93], s[16:17], v[58:59] op_sel_hi:[1,0,1]
	v_pk_mul_f32 v[54:55], v[142:143], v[54:55]
	v_pk_fma_f32 v[104:105], v[68:69], s[16:17], v[52:53] op_sel_hi:[1,0,1]
	v_pk_fma_f32 v[156:157], v[80:81], s[16:17], v[50:51] op_sel_hi:[1,0,1]
	v_pk_mov_b32 v[50:51], v[90:91], v[94:95] op_sel:[1,0]
	v_mov_b32_e32 v52, v90
	v_mov_b32_e32 v53, v95
	v_pk_fma_f32 v[102:103], v[78:79], s[16:17], v[54:55] op_sel_hi:[1,0,1]
	v_pk_add_f32 v[50:51], v[50:51], v[52:53]
	v_pk_mov_b32 v[52:53], v[98:99], v[96:97] op_sel:[1,0]
	v_mov_b32_e32 v54, v98
	v_mov_b32_e32 v55, v97
	v_pk_add_f32 v[52:53], v[52:53], v[54:55]
	v_add_f32_e32 v50, v50, v51
	v_pk_add_f32 v[52:53], v[52:53], v[52:53] op_sel_hi:[0,1]
	v_add_f32_e32 v51, 0, v50
	v_add_f32_e32 v55, v102, v103
	v_add_f32_e32 v57, v100, v101
	v_mov_b32_e32 v54, v156
	v_mov_b32_e32 v56, v157
	v_mov_b32_e32 v52, v104
	v_mov_b32_e32 v50, v105
	v_pk_add_f32 v[54:55], v[54:55], v[56:57]
	v_pk_add_f32 v[50:51], v[52:53], v[50:51]
	s_add_i32 s26, s8, s10
	v_pk_add_f32 v[50:51], v[54:55], v[50:51]
	s_add_i32 s0, s26, 1
	v_add_f32_e32 v50, v50, v51
	ds_bpermute_b32 v51, v1, v50
	s_ashr_i32 s1, s0, 31
	s_lshl_b64 s[30:31], s[0:1], 13
	s_lshl_b64 s[0:1], s[0:1], 11
	v_lshl_add_u64 v[52:53], v[108:109], 0, s[0:1]
	s_waitcnt lgkmcnt(0)
; __device__ __forceinline__ void ln_stats(const f32x4 (&v)[4], float& mean, float& rstd) {
;     float s = 0.f;
; #pragma unroll
;     for (int j = 0; j < 4; ++j) s += (v[j].x + v[j].y) + (v[j].z + v[j].w);
;     mean = wsum(s) * (1.f / D);
;     float s2 = 0.f;
; #pragma unroll
;     for (int j = 0; j < 4; ++j) { const f32x4 d = v[j] - mean; s2 += (d.x * d.x + d.y * d.y) + (d.z * d.z + d.w * d.w); }
;     rstd = 1.f / sqrtf(wsum(s2) * (1.f / D) + LN_EPS);
; __device__ __forceinline__ void phase_row2(const Frame& F, int l) {
;     ...
;             if (i + 1 < 8) { const bf16* yk = (const bf16*)(F.ws + WS_YK) + (size_t)(row + 1) * 4 * D + 8 * lane;
; #pragma unroll
;                 for (int j2 = 0; j2 < 2; ++j2) { nxb[j2] = *(const u32x4*)(XB + (size_t)(row + 1) * D + 512 * j2 + 8 * lane);
; #pragma unroll
;                     for (int k = 0; k < 4; ++k) ny[k][j2] = *(const u32x4*)(yk + k * D + 512 * j2); } }
	v_add_f32_e32 v50, v50, v51
	ds_bpermute_b32 v51, v107, v50
	s_waitcnt lgkmcnt(0)
	v_add_f32_e32 v50, v50, v51
	ds_bpermute_b32 v51, v152, v50
	s_waitcnt lgkmcnt(0)
	v_add_f32_e32 v50, v50, v51
	ds_bpermute_b32 v51, v153, v50
	s_waitcnt lgkmcnt(0)
	v_add_f32_e32 v54, v50, v51
	ds_bpermute_b32 v55, v154, v54
	v_lshl_add_u64 v[50:51], v[112:113], 0, s[30:31]
	v_add_co_u32_e32 v92, vcc, s77, v50
	s_waitcnt lgkmcnt(0)
	v_add_f32_e32 v54, v54, v55
	ds_bpermute_b32 v55, v155, v54
	v_addc_co_u32_e32 v93, vcc, 0, v51, vcc
	s_waitcnt lgkmcnt(0)
	v_add_f32_e32 v62, v54, v55
	v_fmamk_f32 v91, v62, 0xba800000, v91
	v_fmac_f32_e32 v90, 0xba800000, v62
	v_fmamk_f32 v95, v62, 0xba800000, v95
	v_fmac_f32_e32 v94, 0xba800000, v62
	v_pk_mul_f32 v[54:55], v[94:95], v[94:95]
	v_pk_mul_f32 v[56:57], v[90:91], v[90:91]
	v_fmamk_f32 v99, v62, 0xba800000, v99
	v_pk_mov_b32 v[58:59], v[56:57], v[54:55] op_sel:[1,0]
	v_mov_b32_e32 v57, v55
	v_pk_add_f32 v[54:55], v[58:59], v[56:57]
	v_fmac_f32_e32 v98, 0xba800000, v62
	v_fmamk_f32 v97, v62, 0xba800000, v97
	v_fmac_f32_e32 v96, 0xba800000, v62
	v_pk_add_f32 v[54:55], v[54:55], v[54:55] op_sel_hi:[0,1]
	v_pk_mul_f32 v[56:57], v[96:97], v[96:97]
	v_pk_mul_f32 v[58:59], v[98:99], v[98:99]
	v_fmac_f32_e32 v102, 0xba800000, v62
	v_pk_mov_b32 v[60:61], v[58:59], v[56:57] op_sel:[1,0]
	v_mov_b32_e32 v59, v57
	v_fmamk_f32 v103, v62, 0xba800000, v103
	v_fmac_f32_e32 v100, 0xba800000, v62
	v_mul_f32_e32 v54, v102, v102
	v_pk_add_f32 v[56:57], v[60:61], v[58:59]
	v_fmamk_f32 v101, v62, 0xba800000, v101
	v_pk_fma_f32 v[58:59], v[102:103], v[102:103], v[54:55] op_sel_hi:[1,1,0]
	v_mul_f32_e32 v54, v100, v100
	v_pk_add_f32 v[56:57], v[56:57], v[56:57] op_sel_hi:[0,1]
	v_pk_fma_f32 v[60:61], v[100:101], v[100:101], v[54:55] op_sel_hi:[1,1,0]
	v_fmamk_f32 v105, v62, 0xba800000, v105
	v_fmac_f32_e32 v104, 0xba800000, v62
	v_fmamk_f32 v157, v62, 0xba800000, v157
	v_fmac_f32_e32 v156, 0xba800000, v62
	v_mul_f32_e32 v58, v156, v156
	v_mul_f32_e32 v60, v157, v157
	v_mul_f32_e32 v54, v104, v104
	v_mul_f32_e32 v56, v105, v105
	v_pk_add_f32 v[58:59], v[58:59], v[60:61]
	v_pk_add_f32 v[54:55], v[54:55], v[56:57]
	global_load_dwordx4 v[86:89], v[52:53], off nt
	global_load_dwordx4 v[66:69], v[52:53], off offset:1024 nt
	global_load_dwordx4 v[82:85], v[50:51], off nt
	global_load_dwordx4 v[62:65], v[50:51], off offset:1024 nt
	v_pk_add_f32 v[54:55], v[58:59], v[54:55]
	s_nop 0
	v_add_f32_e32 v54, v54, v55
	ds_bpermute_b32 v55, v1, v54
	s_waitcnt lgkmcnt(0)
	v_add_f32_e32 v52, v54, v55
	ds_bpermute_b32 v53, v107, v52
	global_load_dwordx4 v[78:81], v[50:51], off offset:2048 nt
	global_load_dwordx4 v[58:61], v[50:51], off offset:3072 nt
	global_load_dwordx4 v[74:77], v[92:93], off nt
	global_load_dwordx4 v[54:57], v[92:93], off offset:1024 nt
	s_waitcnt lgkmcnt(0)
	v_add_f32_e32 v158, v52, v53
	global_load_dwordx4 v[70:73], v[92:93], off offset:2048 nt
	global_load_dwordx4 v[50:53], v[92:93], off offset:3072 nt
	ds_bpermute_b32 v159, v152, v158
	s_waitcnt lgkmcnt(0)
	v_add_f32_e32 v92, v158, v159
	ds_bpermute_b32 v93, v153, v92
	s_waitcnt lgkmcnt(0)
	v_add_f32_e32 v92, v92, v93
	ds_bpermute_b32 v93, v154, v92
	s_waitcnt lgkmcnt(0)
	v_add_f32_e32 v92, v92, v93
	ds_bpermute_b32 v93, v155, v92
	s_waitcnt lgkmcnt(0)
	v_add_f32_e32 v92, v92, v93
	v_fmamk_f32 v92, v92, 0x3a800000, v226
	v_mul_f32_e32 v93, 0x4f800000, v92
	v_cmp_gt_f32_e32 vcc, s2, v92
	s_nop 1
	v_cndmask_b32_e32 v92, v92, v93, vcc
	v_sqrt_f32_e32 v93, v92
	s_nop 0
	v_add_u32_e32 v158, -1, v93
	v_fma_f32 v159, -v158, v93, v92
	v_cmp_ge_f32_e64 s[0:1], 0, v159
	v_add_u32_e32 v159, 1, v93
	s_nop 0
	v_cndmask_b32_e64 v158, v93, v158, s[0:1]
	v_fma_f32 v93, -v159, v93, v92
	v_cmp_lt_f32_e64 s[0:1], 0, v93
	s_nop 1
	v_cndmask_b32_e64 v93, v158, v159, s[0:1]
	v_mul_f32_e32 v158, 0x37800000, v93
	v_cndmask_b32_e32 v93, v93, v158, vcc
	v_cmp_class_f32_e32 vcc, v92, v227
	s_nop 1
	v_cndmask_b32_e32 v92, v93, v92, vcc
	v_div_scale_f32 v93, s[0:1], v92, v92, 1.0
	v_rcp_f32_e32 v158, v93
	s_mov_b64 s[0:1], -1
	v_fma_f32 v159, -v93, v158, 1.0
	v_fmac_f32_e32 v158, v159, v158
	v_div_scale_f32 v159, vcc, 1.0, v92, 1.0
	v_mul_f32_e32 v160, v159, v158
	v_fma_f32 v161, -v93, v160, v159
	v_fmac_f32_e32 v160, v161, v158
	v_fma_f32 v93, -v93, v160, v159
	v_div_fmas_f32 v93, v93, v158, v160
	v_div_fixup_f32 v158, v93, v92, 1.0
	v_pk_mul_f32 v[90:91], v[90:91], v[158:159] op_sel_hi:[1,0]
	v_pk_mul_f32 v[92:93], v[94:95], v[158:159] op_sel_hi:[1,0]
	v_pk_mul_f32 v[94:95], v[98:99], v[158:159] op_sel_hi:[1,0]
	v_pk_mul_f32 v[96:97], v[96:97], v[158:159] op_sel_hi:[1,0]
	v_pk_mul_f32 v[98:99], v[102:103], v[158:159] op_sel_hi:[1,0]
	v_pk_mul_f32 v[100:101], v[100:101], v[158:159] op_sel_hi:[1,0]
	v_pk_mul_f32 v[102:103], v[156:157], v[158:159] op_sel_hi:[1,0]
	v_pk_mul_f32 v[104:105], v[104:105], v[158:159] op_sel_hi:[1,0]
	v_pk_fma_f32 v[92:93], v[44:45], v[92:93], v[48:49]
	v_pk_fma_f32 v[90:91], v[42:43], v[90:91], v[46:47]
	v_pk_fma_f32 v[96:97], v[36:37], v[96:97], v[40:41]
	v_pk_fma_f32 v[94:95], v[34:35], v[94:95], v[38:39]
	v_pk_fma_f32 v[100:101], v[28:29], v[100:101], v[32:33]
	v_pk_fma_f32 v[98:99], v[26:27], v[98:99], v[30:31]
	v_pk_fma_f32 v[104:105], v[20:21], v[104:105], v[24:25]
	v_pk_fma_f32 v[102:103], v[18:19], v[102:103], v[22:23]
	s_and_b64 vcc, exec, s[28:29]
	s_cbranch_vccz .LBB0_2429
; __device__ __forceinline__ void ada_ln_r(f32x4 (&v)[4], const f32x4 (&sc1)[4], const f32x4 (&sh)[4]) {
;     float mean, rstd; ln_stats(v, mean, rstd);
; #pragma unroll
;     for (int j = 0; j < 4; ++j) v[j] = (v[j] - mean) * rstd * sc1[j] + sh[j];
; __device__ __forceinline__ void phase_row2(const Frame& F, int l) {
;     ...
;             if (l + 1 == DEPTH) store_row8(((float*)F.out) + (size_t)row * D, lane, x);
;             else {
;                 store_row8_bf16(XB + (size_t)row * D, lane, x);
;                 ada_ln_r(x, sc1, sh);
;                 store_row8_bf16(H + (size_t)row * D, lane, x);
;             }
	v_mov_b32_e32 v156, v91
	v_mov_b32_e32 v157, v92
	v_mov_b32_e32 v158, v90
	v_mov_b32_e32 v159, v93
	v_pk_add_f32 v[156:157], v[156:157], v[158:159]
	v_mov_b32_e32 v158, v95
	v_mov_b32_e32 v159, v96
	v_mov_b32_e32 v160, v94
	v_mov_b32_e32 v161, v97
	v_pk_add_f32 v[158:159], v[158:159], v[160:161]
	v_add_f32_e32 v156, v156, v157
	v_pk_add_f32 v[158:159], v[158:159], v[158:159] op_sel_hi:[0,1]
	v_add_f32_e32 v157, 0, v156
	v_add_f32_e32 v161, v98, v99
	v_add_f32_e32 v163, v100, v101
	v_mov_b32_e32 v160, v102
	v_mov_b32_e32 v162, v103
	v_mov_b32_e32 v158, v104
	v_mov_b32_e32 v156, v105
	v_pk_add_f32 v[160:161], v[160:161], v[162:163]
	v_pk_add_f32 v[156:157], v[158:159], v[156:157]
	v_mov_b32_e32 v162, v92
	v_pk_add_f32 v[156:157], v[160:161], v[156:157]
	v_mov_b32_e32 v160, v90
	v_add_f32_e32 v156, v156, v157
	ds_bpermute_b32 v157, v1, v156
	v_mov_b32_e32 v164, v94
	v_mov_b32_e32 v176, v104
	v_mov_b32_e32 v178, v102
	s_ashr_i32 s27, s26, 31
	s_waitcnt lgkmcnt(0)
	v_add_f32_e32 v156, v156, v157
	ds_bpermute_b32 v157, v107, v156
	s_lshl_b64 s[40:41], s[26:27], 11
	s_waitcnt lgkmcnt(0)
	v_add_f32_e32 v156, v156, v157
	ds_bpermute_b32 v157, v152, v156
	s_waitcnt lgkmcnt(0)
	v_add_f32_e32 v156, v156, v157
	ds_bpermute_b32 v157, v153, v156
	s_waitcnt lgkmcnt(0)
	v_add_f32_e32 v156, v156, v157
	ds_bpermute_b32 v157, v154, v156
	s_waitcnt lgkmcnt(0)
	v_add_f32_e32 v156, v156, v157
	ds_bpermute_b32 v157, v155, v156
	s_waitcnt lgkmcnt(0)
	v_add_f32_e32 v180, v156, v157
	v_fmamk_f32 v161, v180, 0xba800000, v91
	v_fmac_f32_e32 v160, 0xba800000, v180
	v_fmamk_f32 v163, v180, 0xba800000, v93
	v_fmac_f32_e32 v162, 0xba800000, v180
	v_pk_mul_f32 v[156:157], v[162:163], v[162:163]
	v_pk_mul_f32 v[158:159], v[160:161], v[160:161]
	v_fmamk_f32 v165, v180, 0xba800000, v95
	v_pk_mov_b32 v[166:167], v[158:159], v[156:157] op_sel:[1,0]
	v_mov_b32_e32 v159, v157
	v_pk_add_f32 v[156:157], v[166:167], v[158:159]
	v_mov_b32_e32 v166, v96
	v_fmac_f32_e32 v164, 0xba800000, v180
	v_fmamk_f32 v167, v180, 0xba800000, v97
	v_fmac_f32_e32 v166, 0xba800000, v180
	v_pk_mul_f32 v[158:159], v[166:167], v[166:167]
	v_pk_mul_f32 v[168:169], v[164:165], v[164:165]
	v_pk_add_f32 v[156:157], v[156:157], v[156:157] op_sel_hi:[0,1]
	v_pk_mov_b32 v[170:171], v[168:169], v[158:159] op_sel:[1,0]
	v_mov_b32_e32 v169, v159
	v_pk_add_f32 v[158:159], v[170:171], v[168:169]
	v_mov_b32_e32 v168, v98
	v_fmac_f32_e32 v168, 0xba800000, v180
	v_mov_b32_e32 v170, v100
	v_fmamk_f32 v169, v180, 0xba800000, v99
	v_fmac_f32_e32 v170, 0xba800000, v180
	v_mul_f32_e32 v156, v168, v168
	v_fmamk_f32 v171, v180, 0xba800000, v101
	v_pk_fma_f32 v[172:173], v[168:169], v[168:169], v[156:157] op_sel_hi:[1,1,0]
	v_mul_f32_e32 v156, v170, v170
	v_pk_add_f32 v[158:159], v[158:159], v[158:159] op_sel_hi:[0,1]
	v_pk_fma_f32 v[174:175], v[170:171], v[170:171], v[156:157] op_sel_hi:[1,1,0]
	v_fmamk_f32 v177, v180, 0xba800000, v105
	v_fmac_f32_e32 v176, 0xba800000, v180
	v_fmamk_f32 v179, v180, 0xba800000, v103
	v_fmac_f32_e32 v178, 0xba800000, v180
	v_mul_f32_e32 v172, v178, v178
	v_mul_f32_e32 v174, v179, v179
	v_mul_f32_e32 v156, v176, v176
	v_mul_f32_e32 v158, v177, v177
	v_pk_add_f32 v[172:173], v[172:173], v[174:175]
	v_pk_add_f32 v[156:157], v[156:157], v[158:159]
	v_cvt_pk_bf16_f32 v158, v94, v95
	v_cvt_pk_bf16_f32 v159, v96, v97
	s_nop 0
	v_pk_add_f32 v[156:157], v[172:173], v[156:157]
	v_lshl_add_u64 v[172:173], v[108:109], 0, s[40:41]
	v_add_f32_e32 v156, v156, v157
	ds_bpermute_b32 v157, v1, v156
	s_waitcnt lgkmcnt(0)
	v_add_f32_e32 v156, v156, v157
	ds_bpermute_b32 v157, v107, v156
	s_waitcnt lgkmcnt(0)
	v_add_f32_e32 v156, v156, v157
	ds_bpermute_b32 v157, v152, v156
	s_waitcnt lgkmcnt(0)
	v_add_f32_e32 v156, v156, v157
	ds_bpermute_b32 v157, v153, v156
	s_waitcnt lgkmcnt(0)
	v_add_f32_e32 v156, v156, v157
	ds_bpermute_b32 v157, v154, v156
	s_waitcnt lgkmcnt(0)
	v_add_f32_e32 v174, v156, v157
	ds_bpermute_b32 v175, v155, v174
	v_cvt_pk_bf16_f32 v156, v90, v91
	v_cvt_pk_bf16_f32 v157, v92, v93
	global_store_dwordx4 v[172:173], v[156:159], off
	s_waitcnt lgkmcnt(0)
	v_add_f32_e32 v174, v174, v175
	v_fmamk_f32 v174, v174, 0x3a800000, v226
	v_mul_f32_e32 v175, 0x4f800000, v174
	v_cmp_gt_f32_e32 vcc, s2, v174
	v_cvt_pk_bf16_f32 v156, v98, v99
	v_cvt_pk_bf16_f32 v157, v100, v101
	s_nop 1
	v_cndmask_b32_e32 v174, v174, v175, vcc
	v_sqrt_f32_e32 v175, v174
	s_nop 0
	v_add_u32_e32 v158, -1, v175
	v_fma_f32 v159, -v158, v175, v174
	v_cmp_ge_f32_e64 s[0:1], 0, v159
	v_add_u32_e32 v159, 1, v175
	s_nop 0
	v_cndmask_b32_e64 v158, v175, v158, s[0:1]
	v_fma_f32 v175, -v159, v175, v174
	v_cmp_lt_f32_e64 s[0:1], 0, v175
	s_nop 1
	v_cndmask_b32_e64 v158, v158, v159, s[0:1]
	v_mul_f32_e32 v159, 0x37800000, v158
	v_cndmask_b32_e32 v158, v158, v159, vcc
	v_cmp_class_f32_e32 vcc, v174, v227
	v_cvt_pk_bf16_f32 v159, v104, v105
	s_nop 1
	v_cndmask_b32_e32 v174, v158, v174, vcc
	v_div_scale_f32 v175, s[0:1], v174, v174, 1.0
	v_rcp_f32_e32 v180, v175
	v_cvt_pk_bf16_f32 v158, v102, v103
	global_store_dwordx4 v[172:173], v[156:159], off offset:1024
	s_nop 1
	v_fma_f32 v156, -v175, v180, 1.0
	v_fmac_f32_e32 v180, v156, v180
	v_div_scale_f32 v156, vcc, 1.0, v174, 1.0
	v_mul_f32_e32 v157, v156, v180
	v_fma_f32 v158, -v175, v157, v156
	v_fmac_f32_e32 v157, v158, v180
	v_fma_f32 v156, -v175, v157, v156
	v_div_fmas_f32 v156, v156, v180, v157
	v_div_fixup_f32 v156, v156, v174, 1.0
	v_pk_mul_f32 v[158:159], v[160:161], v[156:157] op_sel_hi:[1,0]
	v_pk_mul_f32 v[160:161], v[162:163], v[156:157] op_sel_hi:[1,0]
	v_pk_fma_f32 v[158:159], v[128:129], v[158:159], v[14:15]
	v_pk_mul_f32 v[162:163], v[164:165], v[156:157] op_sel_hi:[1,0]
	v_pk_mul_f32 v[164:165], v[166:167], v[156:157] op_sel_hi:[1,0]
	v_pk_mul_f32 v[166:167], v[168:169], v[156:157] op_sel_hi:[1,0]
	v_pk_mul_f32 v[168:169], v[170:171], v[156:157] op_sel_hi:[1,0]
	v_pk_mul_f32 v[170:171], v[178:179], v[156:157] op_sel_hi:[1,0]
	v_pk_mul_f32 v[156:157], v[176:177], v[156:157] op_sel_hi:[1,0]
	v_pk_fma_f32 v[160:161], v[130:131], v[160:161], v[16:17]
	v_pk_fma_f32 v[164:165], v[134:135], v[164:165], v[12:13]
	v_pk_fma_f32 v[162:163], v[132:133], v[162:163], v[10:11]
	v_pk_fma_f32 v[172:173], v[122:123], v[156:157], v[4:5]
	v_lshl_add_u64 v[174:175], v[110:111], 0, s[40:41]
	v_cvt_pk_bf16_f32 v156, v158, v159
	v_cvt_pk_bf16_f32 v157, v160, v161
	v_cvt_pk_bf16_f32 v158, v162, v163
	v_cvt_pk_bf16_f32 v159, v164, v165
	v_pk_fma_f32 v[168:169], v[126:127], v[168:169], v[8:9]
	v_pk_fma_f32 v[166:167], v[124:125], v[166:167], v[6:7]
	v_pk_fma_f32 v[170:171], v[120:121], v[170:171], v[2:3]
	global_store_dwordx4 v[174:175], v[156:159], off
	s_nop 1
	v_cvt_pk_bf16_f32 v156, v166, v167
	v_cvt_pk_bf16_f32 v157, v168, v169
	v_cvt_pk_bf16_f32 v158, v170, v171
	v_cvt_pk_bf16_f32 v159, v172, v173
	global_store_dwordx4 v[174:175], v[156:159], off offset:1024
	s_cbranch_execnz .LBB0_2426
	s_branch .LBB0_2430
